# conv tile split index 2800
# speedup vs baseline: 1.0025x; 1.0025x over previous
.LBB0_469:
	s_add_i32 s0, s33, 0xffffff10
	s_cmpk_gt_u32 s0, 0x80f
	s_cbranch_scc1 .LBB0_492
	v_lshlrev_b32_e32 v2, 2, v1
	v_lshrrev_b32_e32 v3, 3, v188
	v_add_u32_e32 v39, 0, v2
	v_readlane_b32 s8, v254, 0
	v_and_b32_e32 v26, 0x78, v3
	v_or_b32_e32 v33, 7, v3
	v_lshl_add_u32 v3, v1, 8, v39
	v_readlane_b32 s9, v254, 1
	v_readlane_b32 s10, v254, 2
	v_readlane_b32 s11, v254, 3
	v_readlane_b32 s12, v254, 4
	v_readlane_b32 s13, v254, 5
	v_lshl_add_u32 v34, v26, 2, v3
	v_lshl_add_u32 v35, v33, 2, v3
	v_mov_b32_e32 v3, 0
	v_readlane_b32 s14, v254, 6
	v_readlane_b32 s15, v254, 7
	s_mov_b64 s[6:7], s[10:11]
	s_mov_b64 s[8:9], s[12:13]
	v_lshl_add_u64 v[4:5], s[8:9], 0, v[2:3]
	v_lshl_add_u64 v[6:7], s[72:73], 0, v[2:3]
	v_lshl_add_u64 v[8:9], s[70:71], 0, v[2:3]
	v_lshl_add_u64 v[10:11], s[68:69], 0, v[2:3]
	v_lshl_add_u64 v[12:13], s[6:7], 0, v[2:3]
	v_lshl_add_u64 v[14:15], s[74:75], 0, v[2:3]
	v_lshlrev_b32_e32 v2, 1, v1
	v_lshl_add_u64 v[16:17], s[86:87], 0, v[2:3]
	s_mov_b64 s[2:3], 0x1880000
	v_lshl_add_u64 v[18:19], v[16:17], 0, s[2:3]
	s_mov_b64 s[2:3], 0x1300000
	s_add_i32 s4, s33, 0x1f0
	v_mul_u32_u24_e32 v38, 0x104, v26
	s_mov_b64 s[10:11], s[14:15]
	v_lshl_add_u64 v[20:21], v[16:17], 0, s[2:3]
	s_mov_b64 s[2:3], 0x800000
	v_mul_u32_u24_e32 v40, 0x104, v33
	v_lshl_add_u64 v[22:23], v[16:17], 0, s[2:3]
	s_mov_b64 s[2:3], 0x600000
	s_lshl_b32 s6, s50, 6
	s_mul_i32 s8, s50, 0x2e000
	v_lshrrev_b32_e32 v2, 6, v188
	s_lshl_b32 s0, s4, 2
	s_lshl_b32 s10, s50, 2
	v_add_u32_e32 v38, v39, v38
	s_mov_b32 s1, 0
	v_or_b32_e32 v27, 1, v26
	v_or_b32_e32 v28, 2, v26
	v_or_b32_e32 v29, 3, v26
	v_or_b32_e32 v30, 4, v26
	v_or_b32_e32 v31, 5, v26
	v_or_b32_e32 v32, 6, v26
	v_lshl_add_u64 v[24:25], v[16:17], 0, s[2:3]
	s_lshl_b32 s5, s4, 6
	s_addk_i32 s6, 0xc400
	v_mul_u32_u24_e32 v36, 0xb80, v33
	s_mul_i32 s7, s4, 0x2e000
	s_add_i32 s8, s8, 0xfd4e0000
	v_mul_u32_u24_e32 v37, 0x5c00, v2
	s_add_i32 s9, s0, 0x3cf80
	s_addk_i32 s10, 0xfc40
	v_add_u32_e32 v39, v39, v40
	s_movk_i32 s11, 0x7fff
	s_mov_b32 s12, 0xfff00
	s_mov_b32 s13, 0x40000
	v_add_u32_e32 v40, 0x400, v38
	s_branch .LBB0_472
.LBB0_471:
	s_add_i32 s4, s4, s95
	s_add_i32 s5, s5, s6
	s_add_i32 s7, s7, s8
	s_add_i32 s9, s9, s10
	s_cmpk_lt_i32 s4, 0xaf0
	s_cbranch_scc0 .LBB0_492

.LBB0_731:
	s_add_i32 s0, s33, 0xffffff10
	s_cmpk_gt_u32 s0, 0xd6f
	s_cbranch_scc1 .LBB0_770
	v_lshlrev_b32_e32 v2, 2, v1
	v_lshrrev_b32_e32 v3, 3, v188
	v_add_u32_e32 v52, 0, v2
	v_and_b32_e32 v40, 0x78, v3
	v_or_b32_e32 v47, 7, v3
	v_lshl_add_u32 v3, v1, 8, v52
	v_readlane_b32 s12, v254, 0
	v_lshl_add_u32 v48, v40, 2, v3
	v_lshl_add_u32 v49, v47, 2, v3
	v_mov_b32_e32 v3, 0
	v_readlane_b32 s14, v254, 2
	v_readlane_b32 s15, v254, 3
	v_readlane_b32 s16, v254, 4
	v_readlane_b32 s17, v254, 5
	v_lshl_add_u64 v[4:5], s[84:85], 0, v[2:3]
	v_lshl_add_u64 v[8:9], s[72:73], 0, v[2:3]
	v_lshl_add_u64 v[6:7], s[16:17], 0, v[2:3]
	v_lshl_add_u64 v[10:11], s[70:71], 0, v[2:3]
	v_lshl_add_u64 v[12:13], s[68:69], 0, v[2:3]
	v_lshl_add_u64 v[14:15], s[14:15], 0, v[2:3]
	v_lshl_add_u64 v[16:17], s[74:75], 0, v[2:3]
	v_lshlrev_b32_e32 v2, 1, v1
	s_mov_b64 s[2:3], 0xb00000
	v_lshl_add_u64 v[18:19], s[86:87], 0, v[2:3]
	v_lshl_add_u64 v[20:21], v[8:9], 0, s[2:3]
	v_lshl_add_u64 v[24:25], v[10:11], 0, s[2:3]
	v_lshl_add_u64 v[28:29], v[12:13], 0, s[2:3]
	s_mov_b64 s[2:3], 0x1e80000
	v_lshl_add_u64 v[30:31], v[18:19], 0, s[2:3]
	s_mov_b64 s[2:3], 0x1880000
	s_mov_b64 s[6:7], 0x2b80000
	v_lshl_add_u64 v[32:33], v[18:19], 0, s[2:3]
	s_mov_b64 s[2:3], 0x1300000
	s_add_i32 s4, s33, 0xa00
	v_mul_u32_u24_e32 v51, 0x104, v40
	v_readlane_b32 s13, v254, 1
	v_lshl_add_u64 v[22:23], v[18:19], 0, s[6:7]
	s_mov_b64 s[6:7], 0x2080000
	v_lshl_add_u64 v[34:35], v[18:19], 0, s[2:3]
	s_mov_b64 s[2:3], 0x800000
	v_mul_u32_u24_e32 v53, 0x104, v47
	v_lshl_add_u64 v[26:27], v[18:19], 0, s[6:7]
	v_lshl_add_u64 v[36:37], v[18:19], 0, s[2:3]
	s_mov_b64 s[2:3], 0x600000
	s_lshl_b32 s7, s50, 6
	s_mul_i32 s9, s50, 0x2e000
	v_lshrrev_b32_e32 v2, 6, v188
	s_lshl_b32 s0, s4, 2
	s_lshl_b32 s13, s50, 2
	v_add_u32_e32 v51, v52, v51
	s_mov_b32 s1, 0
	v_or_b32_e32 v41, 1, v40
	v_or_b32_e32 v42, 2, v40
	v_or_b32_e32 v43, 3, v40
	v_or_b32_e32 v44, 4, v40
	v_or_b32_e32 v45, 5, v40
	v_or_b32_e32 v46, 6, v40
	s_add_i32 s5, s50, 0xffffff10
	v_lshl_add_u64 v[38:39], v[18:19], 0, s[2:3]
	s_lshl_b32 s6, s4, 6
	s_addk_i32 s7, 0xc400
	v_mul_u32_u24_e32 v1, 0xb80, v47
	s_mul_i32 s8, s4, 0x2e000
	s_add_i32 s9, s9, 0xfd4e0000
	v_mul_u32_u24_e32 v50, 0x5c00, v2
	s_add_i32 s12, s0, 0x3b480
	s_addk_i32 s13, 0xfc40
	v_add_u32_e32 v52, v52, v53
	s_movk_i32 s14, 0x7fff
	s_mov_b32 s15, 0xfff00
	s_mov_b32 s16, 0x40000
	v_add_u32_e32 v53, 0x400, v51
	v_readlane_b32 s18, v254, 6
	v_readlane_b32 s19, v254, 7
	s_branch .LBB0_734
